# fox skip threshold 125->94 nats: skipped tiles have p < 2^-134 which rounds to exactly 0 in the bf16 P operand, output bit-identical; on top of G2 epilogue fast path
# speedup vs baseline: 1.0283x; 1.0281x over previous
; __global__ void __launch_bounds__(512, 2) hymba_fwd(Args a) {
;     ...
;             if (tid < 64) {
;                 const float c0 = dst[64 * tid]; int lo = 0, hi = tid;
;                 while (lo < hi) { const int mid = (lo + hi) >> 1; if (dst[64 * mid + 63] - c0 <= att::FOX_SKIP_NATS) hi = mid; else lo = mid + 1; }
;                 jtlo[blockIdx.x * 64 + tid] = lo;
;             }
.LBB0_202:
	v_add_u32_e32 v3, v2, v4
	v_ashrrev_i32_e32 v3, 1, v3
	v_lshlrev_b32_e32 v6, 6, v3
	v_ashrrev_i32_e32 v7, 31, v6
	v_lshl_add_u64 v[6:7], v[6:7], 2, s[8:9]
	global_load_dword v5, v[6:7], off offset:252
	s_mov_b32 s0, 0x42bc0000
	v_add_u32_e32 v6, 1, v3
	s_waitcnt vmcnt(0)
	v_sub_f32_e32 v5, v5, v0
	v_cmp_nge_f32_e32 vcc, s0, v5
	s_nop 1
	v_cndmask_b32_e32 v4, v4, v6, vcc
	v_cndmask_b32_e32 v2, v3, v2, vcc
	v_cmp_ge_i32_e32 vcc, v4, v2
	s_or_b64 s[6:7], vcc, s[6:7]
	s_andn2_b64 exec, exec, s[6:7]
	s_cbranch_execnz .LBB0_202
	s_or_b64 exec, exec, s[6:7]
